# GLA tiles: per-token decay LDS reads requested in groups of 8 (one wait per group) in the exp sections
# baseline (speedup 1.0000x reference)
; __device__ __forceinline__ bf16_t f2bf(float x) { return (bf16_t)(cvt_pk_bf16(x, 0.f) & 0xffffu); }
; __device__ __forceinline__ void gla_a_tile(LAS unsigned char* lds, const GlaArgs& A, int tile, int tid) {
;     ...
;           if (cc < 128) { const int d = cc - 64;
; #pragma unroll
;               for (int e = 0; e < 8; ++e) { const int i = i0 + 8 * e;
; #pragma unroll
;                   for (int q = 0; q < 4; ++q) KDT[(d + q) * 72 + i] = f2bf(o[e][q] * __expf(GC[63 * 65 + d + q] - GC[i * 65 + d + q])); } }
.LBB0_195:
	s_andn2_saveexec_b64 s[20:21], s[20:21]
	s_cbranch_execz .LBB0_197
	v_add_u32_e32 v2, 0x3efc, v93
	v_add_u32_e32 v10, v122, v120
	v_add_u32_e32 v154, 0x3efc, v93
	ds_read2_b32 v[156:157], v154 offset1:1
	v_add_u32_e32 v155, v122, v120
	ds_read2_b32 v[158:159], v155 offset1:1
	v_add_u32_e32 v160, 0x3f04, v93
	ds_read2_b32 v[162:163], v160 offset1:1
	ds_read2_b32 v[164:165], v155 offset0:2 offset1:3
	v_add_u32_e32 v161, v122, v123
	ds_read2_b32 v[166:167], v161 offset1:1
	ds_read2_b32 v[168:169], v161 offset0:2 offset1:3
	v_add_u32_e32 v170, v93, v123
	v_add_u32_e32 v171, 0x720, v170
	ds_read2_b32 v[172:173], v171 offset1:1
	v_add_u32_e32 v174, 0x728, v170
	ds_read2_b32 v[176:177], v174 offset1:1
	s_waitcnt lgkmcnt(0)
	v_add_u32_e32 v12, v122, v123
	v_sub_f32_e32 v2, v156, v158
	v_mul_f32_e32 v2, 0x3fb8aa3b, v2
	v_exp_f32_e32 v2, v2
	s_nop 0
	v_mul_f32_e32 v2, v138, v2
	v_cvt_pk_bf16_f32 v2, v2, s0
	ds_write_b16 v133, v2 offset:16640
	v_sub_f32_e32 v2, v157, v159
	v_mul_f32_e32 v2, 0x3fb8aa3b, v2
	v_exp_f32_e32 v2, v2
	s_nop 0
	v_mul_f32_e32 v2, v137, v2
	v_cvt_pk_bf16_f32 v2, v2, s0
	ds_write_b16 v0, v2 offset:7568
	v_add_u32_e32 v2, 0x3f04, v93
	v_sub_f32_e32 v10, v162, v164
	v_mul_f32_e32 v10, 0x3fb8aa3b, v10
	v_exp_f32_e32 v10, v10
	s_nop 0
	v_mul_f32_e32 v10, v136, v10
	v_cvt_pk_bf16_f32 v10, v10, s0
	ds_write_b16 v0, v10 offset:7712
	v_sub_f32_e32 v10, v163, v165
	v_mul_f32_e32 v10, 0x3fb8aa3b, v10
	v_exp_f32_e32 v10, v10
	s_nop 0
	v_mul_f32_e32 v10, v135, v10
	v_cvt_pk_bf16_f32 v10, v10, s0
	ds_write_b16 v0, v10 offset:7856
	v_sub_f32_e32 v10, v156, v166
	v_mul_f32_e32 v10, 0x3fb8aa3b, v10
	v_exp_f32_e32 v10, v10
	s_nop 0
	v_mul_f32_e32 v10, v113, v10
	v_cvt_pk_bf16_f32 v10, v10, s0
	ds_write_b16 v133, v10 offset:16656
	v_sub_f32_e32 v10, v157, v167
	v_mul_f32_e32 v10, 0x3fb8aa3b, v10
	v_exp_f32_e32 v10, v10
	s_nop 0
	v_mul_f32_e32 v10, v112, v10
	v_cvt_pk_bf16_f32 v10, v10, s0
	ds_write_b16 v0, v10 offset:7584
	v_sub_f32_e32 v10, v162, v168
	v_mul_f32_e32 v10, 0x3fb8aa3b, v10
	v_exp_f32_e32 v10, v10
	s_nop 0
	v_mul_f32_e32 v10, v111, v10
	v_cvt_pk_bf16_f32 v10, v10, s0
	ds_write_b16 v0, v10 offset:7728
	v_sub_f32_e32 v10, v163, v169
	v_mul_f32_e32 v10, 0x3fb8aa3b, v10
	v_exp_f32_e32 v10, v10
	s_nop 0
	v_mul_f32_e32 v10, v110, v10
	v_cvt_pk_bf16_f32 v10, v10, s0
	ds_write_b16 v0, v10 offset:7872
	v_add_u32_e32 v10, v93, v123
	v_add_u32_e32 v11, 0x720, v10
	v_sub_f32_e32 v11, v156, v172
	v_mul_f32_e32 v11, 0x3fb8aa3b, v11
	v_exp_f32_e32 v11, v11
	s_nop 0
	v_mul_f32_e32 v11, v105, v11
	v_cvt_pk_bf16_f32 v11, v11, s0
	ds_write_b16 v133, v11 offset:16672
	v_sub_f32_e32 v11, v157, v173
	v_mul_f32_e32 v11, 0x3fb8aa3b, v11
	v_exp_f32_e32 v11, v11
	s_nop 0
	v_mul_f32_e32 v11, v104, v11
	v_cvt_pk_bf16_f32 v11, v11, s0
	ds_write_b16 v0, v11 offset:7600
	v_add_u32_e32 v11, 0x728, v10
	v_sub_f32_e32 v11, v162, v176
	v_mul_f32_e32 v11, 0x3fb8aa3b, v11
	v_exp_f32_e32 v11, v11
	s_nop 0
	v_mul_f32_e32 v11, v103, v11
	v_cvt_pk_bf16_f32 v11, v11, s0
	ds_write_b16 v0, v11 offset:7744
	v_sub_f32_e32 v11, v163, v177
	v_mul_f32_e32 v11, 0x3fb8aa3b, v11
	v_exp_f32_e32 v11, v11
	s_nop 0
	v_mul_f32_e32 v11, v102, v11
	v_cvt_pk_bf16_f32 v11, v11, s0
	ds_write_b16 v0, v11 offset:7888
	v_add_u32_e32 v11, 0xf40, v10
	v_add_u32_e32 v154, v93, v123
	v_add_u32_e32 v155, 0xf40, v154
	ds_read2_b32 v[158:159], v155 offset1:1
	v_add_u32_e32 v160, 0xf48, v154
	ds_read2_b32 v[164:165], v160 offset1:1
	v_add_u32_e32 v161, 0x1760, v154
	ds_read2_b32 v[166:167], v161 offset1:1
	v_add_u32_e32 v168, 0x1768, v154
	ds_read2_b32 v[170:171], v168 offset1:1
	v_add_u32_e32 v169, 0x1f80, v154
	ds_read2_b32 v[172:173], v169 offset1:1
	v_add_u32_e32 v174, 0x1f88, v154
	ds_read2_b32 v[178:179], v174 offset1:1
	v_add_u32_e32 v175, 0x27a0, v154
	ds_read2_b32 v[180:181], v175 offset1:1
	v_add_u32_e32 v182, 0x27a8, v154
	ds_read2_b32 v[184:185], v182 offset1:1
	s_waitcnt lgkmcnt(0)
; __device__ __forceinline__ bf16_t f2bf(float x) { return (bf16_t)(cvt_pk_bf16(x, 0.f) & 0xffffu); }
; __device__ __forceinline__ void gla_a_tile(LAS unsigned char* lds, const GlaArgs& A, int tile, int tid) {
;     ...
;           if (cc < 128) { const int d = cc - 64;
; #pragma unroll
;               for (int e = 0; e < 8; ++e) { const int i = i0 + 8 * e;
; #pragma unroll
;                   for (int q = 0; q < 4; ++q) KDT[(d + q) * 72 + i] = f2bf(o[e][q] * __expf(GC[63 * 65 + d + q] - GC[i * 65 + d + q])); } }
	v_sub_f32_e32 v11, v156, v158
	v_mul_f32_e32 v11, 0x3fb8aa3b, v11
	v_exp_f32_e32 v11, v11
	s_nop 0
	v_mul_f32_e32 v11, v53, v11
	v_cvt_pk_bf16_f32 v11, v11, s0
	ds_write_b16 v133, v11 offset:16688
	v_sub_f32_e32 v11, v157, v159
	v_mul_f32_e32 v11, 0x3fb8aa3b, v11
	v_exp_f32_e32 v11, v11
	s_nop 0
	v_mul_f32_e32 v11, v52, v11
	v_cvt_pk_bf16_f32 v11, v11, s0
	ds_write_b16 v0, v11 offset:7616
	v_add_u32_e32 v11, 0xf48, v10
	v_sub_f32_e32 v11, v162, v164
	v_mul_f32_e32 v11, 0x3fb8aa3b, v11
	v_exp_f32_e32 v11, v11
	s_nop 0
	v_mul_f32_e32 v11, v51, v11
	v_cvt_pk_bf16_f32 v11, v11, s0
	ds_write_b16 v0, v11 offset:7760
	v_sub_f32_e32 v11, v163, v165
	v_mul_f32_e32 v11, 0x3fb8aa3b, v11
	v_exp_f32_e32 v11, v11
	s_nop 0
	v_mul_f32_e32 v11, v50, v11
	v_cvt_pk_bf16_f32 v11, v11, s0
	ds_write_b16 v0, v11 offset:7904
	v_add_u32_e32 v11, 0x1760, v10
	v_sub_f32_e32 v11, v156, v166
	v_mul_f32_e32 v11, 0x3fb8aa3b, v11
	v_exp_f32_e32 v11, v11
	s_nop 0
	v_mul_f32_e32 v11, v45, v11
	v_cvt_pk_bf16_f32 v11, v11, s0
	ds_write_b16 v133, v11 offset:16704
	v_sub_f32_e32 v11, v157, v167
	v_mul_f32_e32 v11, 0x3fb8aa3b, v11
	v_exp_f32_e32 v11, v11
	s_nop 0
	v_mul_f32_e32 v11, v44, v11
	v_cvt_pk_bf16_f32 v11, v11, s0
	ds_write_b16 v0, v11 offset:7632
	v_add_u32_e32 v11, 0x1768, v10
	v_sub_f32_e32 v11, v162, v170
	v_mul_f32_e32 v11, 0x3fb8aa3b, v11
	v_exp_f32_e32 v11, v11
	s_nop 0
	v_mul_f32_e32 v11, v43, v11
	v_cvt_pk_bf16_f32 v11, v11, s0
	ds_write_b16 v0, v11 offset:7776
	v_sub_f32_e32 v11, v163, v171
	v_mul_f32_e32 v11, 0x3fb8aa3b, v11
	v_exp_f32_e32 v11, v11
	s_nop 0
	v_mul_f32_e32 v11, v42, v11
	v_cvt_pk_bf16_f32 v11, v11, s0
	ds_write_b16 v0, v11 offset:7920
	v_add_u32_e32 v11, 0x1f80, v10
	v_sub_f32_e32 v11, v156, v172
	v_mul_f32_e32 v11, 0x3fb8aa3b, v11
	v_exp_f32_e32 v11, v11
	s_nop 0
	v_mul_f32_e32 v11, v37, v11
	v_cvt_pk_bf16_f32 v11, v11, s0
	ds_write_b16 v133, v11 offset:16720
	v_sub_f32_e32 v11, v157, v173
	v_mul_f32_e32 v11, 0x3fb8aa3b, v11
	v_exp_f32_e32 v11, v11
	s_nop 0
	v_mul_f32_e32 v11, v36, v11
	v_cvt_pk_bf16_f32 v11, v11, s0
	ds_write_b16 v0, v11 offset:7648
	v_add_u32_e32 v11, 0x1f88, v10
	v_sub_f32_e32 v11, v162, v178
	v_mul_f32_e32 v11, 0x3fb8aa3b, v11
	v_exp_f32_e32 v11, v11
	s_nop 0
	v_mul_f32_e32 v11, v35, v11
	v_cvt_pk_bf16_f32 v11, v11, s0
	ds_write_b16 v0, v11 offset:7792
	v_sub_f32_e32 v11, v163, v179
	v_mul_f32_e32 v11, 0x3fb8aa3b, v11
	v_exp_f32_e32 v11, v11
	s_nop 0
	v_mul_f32_e32 v11, v34, v11
	v_cvt_pk_bf16_f32 v11, v11, s0
	ds_write_b16 v0, v11 offset:7936
	v_add_u32_e32 v11, 0x27a0, v10
	v_sub_f32_e32 v11, v156, v180
	v_mul_f32_e32 v11, 0x3fb8aa3b, v11
	v_exp_f32_e32 v11, v11
	s_nop 0
	v_mul_f32_e32 v11, v29, v11
	v_cvt_pk_bf16_f32 v11, v11, s0
	ds_write_b16 v133, v11 offset:16736
	v_sub_f32_e32 v11, v157, v181
	v_mul_f32_e32 v11, 0x3fb8aa3b, v11
	v_exp_f32_e32 v11, v11
	s_nop 0
	v_mul_f32_e32 v11, v28, v11
	v_cvt_pk_bf16_f32 v11, v11, s0
	ds_write_b16 v0, v11 offset:7664
	v_add_u32_e32 v11, 0x27a8, v10
	v_sub_f32_e32 v11, v162, v184
	v_mul_f32_e32 v11, 0x3fb8aa3b, v11
	v_exp_f32_e32 v11, v11
	s_nop 0
	v_mul_f32_e32 v11, v27, v11
	v_cvt_pk_bf16_f32 v11, v11, s0
	ds_write_b16 v0, v11 offset:7808
	v_sub_f32_e32 v11, v163, v185
	v_mul_f32_e32 v11, 0x3fb8aa3b, v11
	v_exp_f32_e32 v11, v11
	s_nop 0
	v_mul_f32_e32 v11, v26, v11
	v_cvt_pk_bf16_f32 v11, v11, s0
	ds_write_b16 v0, v11 offset:7952
	v_add_u32_e32 v11, 0x2fc0, v10
	v_add_u32_e32 v154, v93, v123
	v_add_u32_e32 v155, 0x2fc0, v154
	ds_read2_b32 v[158:159], v155 offset1:1
	v_add_u32_e32 v160, 0x2fc8, v154
	ds_read2_b32 v[164:165], v160 offset1:1
	s_waitcnt lgkmcnt(0)
	v_sub_f32_e32 v4, v156, v158
	v_mul_f32_e32 v4, 0x3fb8aa3b, v4
	v_exp_f32_e32 v4, v4
	s_nop 0
	v_mul_f32_e32 v4, v9, v4
	v_cvt_pk_bf16_f32 v4, v4, s0
	ds_write_b16 v133, v4 offset:16752
	v_sub_f32_e32 v4, v157, v159
	v_mul_f32_e32 v4, 0x3fb8aa3b, v4
	v_exp_f32_e32 v4, v4
	s_nop 0
	v_mul_f32_e32 v4, v8, v4
	v_cvt_pk_bf16_f32 v4, v4, s0
	ds_write_b16 v0, v4 offset:7680
	v_add_u32_e32 v4, 0x2fc8, v10
	v_sub_f32_e32 v2, v162, v164
	v_mul_f32_e32 v2, 0x3fb8aa3b, v2
	v_exp_f32_e32 v2, v2
	s_nop 0
	v_mul_f32_e32 v2, v7, v2
	v_cvt_pk_bf16_f32 v2, v2, s0
	ds_write_b16 v0, v2 offset:7824
	v_sub_f32_e32 v2, v163, v165
	v_mul_f32_e32 v2, 0x3fb8aa3b, v2
	v_exp_f32_e32 v2, v2
	s_nop 0
	v_mul_f32_e32 v2, v6, v2
	v_cvt_pk_bf16_f32 v2, v2, s0
	ds_write_b16 v0, v2 offset:7968
	v_mov_b32_e32 v3, v163
	v_mov_b32_e32 v4, v164
	v_mov_b32_e32 v5, v165
	v_mov_b32_e32 v12, v158
	v_mov_b32_e32 v13, v159

; #define LAS __attribute__((address_space(3)))
; __device__ __forceinline__ unsigned cvt_pk_bf16(float lo, float hi) { const f32x2 v = {lo, hi}; const bf16x2_t r = __builtin_convertvector(v, bf16x2_t); return __builtin_bit_cast(unsigned, r); }
; __device__ __forceinline__ void gla_c_tile(LAS unsigned char* lds, const GlaArgs& A, int tile, int tid) {
;     ...
;       if (cc < 128) { const int d = cc & 63; const bool isq = cc < 64; LAS bf16_t* T1 = isq ? QG : KR; LAS bf16_t* T2 = isq ? QR : KG; const float sc = isq ? 0.125f : 1.0f;
; #pragma unroll
;           for (int e = 0; e < 8; ++e) { const int i = i0 + 8 * e; f32x4 x1, x2;
; #pragma unroll
;               for (int q = 0; q < 4; ++q) { const float eg = __expf(GC[i * 65 + d + q]); const float x = o[e][q] * sc; x1[q] = x * eg; x2[q] = x / eg; }
;               u32x2 w1, w2; w1.x = cvt_pk_bf16(x1[0], x1[1]); w1.y = cvt_pk_bf16(x1[2], x1[3]); w2.x = cvt_pk_bf16(x2[0], x2[1]); w2.y = cvt_pk_bf16(x2[2], x2[3]);
;               *(LAS u32x2*)(T1 + i * 72 + d) = w1; *(LAS u32x2*)(T2 + i * 72 + d) = w2; } }
.LBB0_312:
	s_andn2_saveexec_b64 s[38:39], s[38:39]
	s_cbranch_execz .LBB0_314
	v_add_u32_e32 v16, v139, v133
	v_add_u32_e32 v126, v139, v133
	ds_read2_b32 v[128:129], v126 offset1:1
	ds_read2_b32 v[130:131], v126 offset0:2 offset1:3
	ds_read2_b32 v[174:175], v147 offset1:1
	ds_read2_b32 v[176:177], v147 offset0:2 offset1:3
	v_add_u32_e32 v127, 0x820, v147
	ds_read2_b32 v[178:179], v127 offset1:1
	v_add_u32_e32 v180, 0x828, v147
	ds_read2_b32 v[182:183], v180 offset1:1
	v_add_u32_e32 v181, 0x1040, v147
	ds_read2_b32 v[184:185], v181 offset1:1
	v_add_u32_e32 v186, 0x1048, v147
	ds_read2_b32 v[188:189], v186 offset1:1
	s_waitcnt lgkmcnt(0)
	v_pk_mul_f32 v[14:15], v[98:99], v[50:51]
	v_pk_mul_f32 v[6:7], v[98:99], v[6:7]
	v_pk_mul_f32 v[2:3], v[98:99], v[2:3]
	v_mul_f32_e32 v10, 0x3fb8aa3b, v128
	v_exp_f32_e32 v12, v10
	v_mul_f32_e32 v10, 0x3fb8aa3b, v129
	v_exp_f32_e32 v13, v10
	s_nop 0
	v_div_scale_f32 v17, s[72:73], v13, v13, v15
	v_rcp_f32_e32 v40, v17
	v_pk_mul_f32 v[10:11], v[14:15], v[12:13]
	v_fma_f32 v41, -v17, v40, 1.0
	v_fmac_f32_e32 v40, v41, v40
	v_div_scale_f32 v41, vcc, v15, v13, v15
	v_mul_f32_e32 v42, v41, v40
	v_fma_f32 v43, -v17, v42, v41
	v_fmac_f32_e32 v42, v43, v40
	v_fma_f32 v17, -v17, v42, v41
	v_div_fmas_f32 v17, v17, v40, v42
	v_div_fixup_f32 v40, v17, v13, v15
	v_div_scale_f32 v13, s[72:73], v12, v12, v14
	v_rcp_f32_e32 v15, v13
	v_cvt_pk_bf16_f32 v10, v10, v11
	v_fma_f32 v17, -v13, v15, 1.0
	v_fmac_f32_e32 v15, v17, v15
	v_div_scale_f32 v17, vcc, v14, v12, v14
	v_mul_f32_e32 v41, v17, v15
	v_fma_f32 v42, -v13, v41, v17
	v_fmac_f32_e32 v41, v42, v15
	v_fma_f32 v13, -v13, v41, v17
	v_div_fmas_f32 v13, v13, v15, v41
	v_div_fixup_f32 v41, v13, v12, v14
	v_pk_mul_f32 v[14:15], v[98:99], v[38:39]
	v_mul_f32_e32 v13, 0x3fb8aa3b, v131
	v_exp_f32_e32 v13, v13
	v_mul_f32_e32 v12, 0x3fb8aa3b, v130
	v_exp_f32_e32 v12, v12
	v_div_scale_f32 v38, s[72:73], v13, v13, v15
	v_rcp_f32_e32 v39, v38
	v_pk_mul_f32 v[16:17], v[14:15], v[12:13]
	v_fma_f32 v42, -v38, v39, 1.0
	v_fmac_f32_e32 v39, v42, v39
	v_div_scale_f32 v42, vcc, v15, v13, v15
	v_mul_f32_e32 v43, v42, v39
	v_fma_f32 v44, -v38, v43, v42
	v_fmac_f32_e32 v43, v44, v39
	v_fma_f32 v38, -v38, v43, v42
	v_div_fmas_f32 v38, v38, v39, v43
	v_div_fixup_f32 v13, v38, v13, v15
	v_div_scale_f32 v15, s[72:73], v12, v12, v14
	v_rcp_f32_e32 v38, v15
	v_cvt_pk_bf16_f32 v11, v16, v17
	v_fma_f32 v39, -v15, v38, 1.0
	v_fmac_f32_e32 v38, v39, v38
	v_div_scale_f32 v39, vcc, v14, v12, v14
	v_mul_f32_e32 v42, v39, v38
	v_fma_f32 v43, -v15, v42, v39
	v_fmac_f32_e32 v42, v43, v38
	v_fma_f32 v15, -v15, v42, v39
	v_div_fmas_f32 v15, v15, v38, v42
	v_div_fixup_f32 v14, v15, v12, v14
	v_cvt_pk_bf16_f32 v12, v41, v40
	v_cvt_pk_bf16_f32 v13, v14, v13
	ds_write_b64 v140, v[10:11]
	ds_write_b64 v141, v[12:13]
	v_pk_mul_f32 v[14:15], v[98:99], v[36:37]
	v_mul_f32_e32 v10, 0x3fb8aa3b, v174
	v_exp_f32_e32 v12, v10
	v_mul_f32_e32 v10, 0x3fb8aa3b, v175
	v_exp_f32_e32 v13, v10
	s_nop 0
	v_div_scale_f32 v16, s[72:73], v13, v13, v15
	v_rcp_f32_e32 v17, v16
	v_pk_mul_f32 v[10:11], v[14:15], v[12:13]
	v_fma_f32 v36, -v16, v17, 1.0
	v_fmac_f32_e32 v17, v36, v17
	v_div_scale_f32 v36, vcc, v15, v13, v15
	v_mul_f32_e32 v37, v36, v17
	v_fma_f32 v38, -v16, v37, v36
	v_fmac_f32_e32 v37, v38, v17
	v_fma_f32 v16, -v16, v37, v36
	v_div_fmas_f32 v16, v16, v17, v37
	v_div_fixup_f32 v36, v16, v13, v15
	v_div_scale_f32 v13, s[72:73], v12, v12, v14
	v_rcp_f32_e32 v15, v13
	v_cvt_pk_bf16_f32 v10, v10, v11
	v_fma_f32 v16, -v13, v15, 1.0
	v_fmac_f32_e32 v15, v16, v15
	v_div_scale_f32 v16, vcc, v14, v12, v14
	v_mul_f32_e32 v17, v16, v15
	v_fma_f32 v37, -v13, v17, v16
	v_fmac_f32_e32 v17, v37, v15
	v_fma_f32 v13, -v13, v17, v16
	v_div_fmas_f32 v13, v13, v15, v17
	v_div_fixup_f32 v37, v13, v12, v14
	v_pk_mul_f32 v[14:15], v[98:99], v[32:33]
	v_mul_f32_e32 v13, 0x3fb8aa3b, v177
	v_exp_f32_e32 v13, v13
	v_mul_f32_e32 v12, 0x3fb8aa3b, v176
	v_exp_f32_e32 v12, v12
	v_div_scale_f32 v32, s[72:73], v13, v13, v15
	v_rcp_f32_e32 v33, v32
	v_pk_mul_f32 v[16:17], v[14:15], v[12:13]
	v_fma_f32 v38, -v32, v33, 1.0
	v_fmac_f32_e32 v33, v38, v33
	v_div_scale_f32 v38, vcc, v15, v13, v15
	v_mul_f32_e32 v39, v38, v33
	v_fma_f32 v40, -v32, v39, v38
	v_fmac_f32_e32 v39, v40, v33
	v_fma_f32 v32, -v32, v39, v38
	v_div_fmas_f32 v32, v32, v33, v39
	v_div_fixup_f32 v13, v32, v13, v15
	v_div_scale_f32 v15, s[72:73], v12, v12, v14
	v_rcp_f32_e32 v32, v15
	v_cvt_pk_bf16_f32 v11, v16, v17
	v_fma_f32 v33, -v15, v32, 1.0
	v_fmac_f32_e32 v32, v33, v32
	v_div_scale_f32 v33, vcc, v14, v12, v14
	v_mul_f32_e32 v38, v33, v32
	v_fma_f32 v39, -v15, v38, v33
	v_fmac_f32_e32 v38, v39, v32
	v_fma_f32 v15, -v15, v38, v33
	v_div_fmas_f32 v15, v15, v32, v38
	v_div_fixup_f32 v14, v15, v12, v14
	v_cvt_pk_bf16_f32 v12, v37, v36
	v_cvt_pk_bf16_f32 v13, v14, v13
	ds_write_b64 v140, v[10:11] offset:1152
	ds_write_b64 v141, v[12:13] offset:1152
	v_add_u32_e32 v10, 0x820, v147
	v_pk_mul_f32 v[14:15], v[98:99], v[34:35]
	v_mul_f32_e32 v10, 0x3fb8aa3b, v178
	v_exp_f32_e32 v12, v10
	v_mul_f32_e32 v10, 0x3fb8aa3b, v179
	v_exp_f32_e32 v13, v10
	s_nop 0
	v_div_scale_f32 v16, s[72:73], v13, v13, v15
	v_rcp_f32_e32 v17, v16
	v_pk_mul_f32 v[10:11], v[14:15], v[12:13]
	v_fma_f32 v32, -v16, v17, 1.0
	v_fmac_f32_e32 v17, v32, v17
	v_div_scale_f32 v32, vcc, v15, v13, v15
	v_mul_f32_e32 v33, v32, v17
	v_fma_f32 v34, -v16, v33, v32
	v_fmac_f32_e32 v33, v34, v17
	v_fma_f32 v16, -v16, v33, v32
	v_div_fmas_f32 v16, v16, v17, v33
	v_div_fixup_f32 v32, v16, v13, v15
	v_div_scale_f32 v13, s[72:73], v12, v12, v14
	v_rcp_f32_e32 v15, v13
	v_cvt_pk_bf16_f32 v10, v10, v11
	v_fma_f32 v16, -v13, v15, 1.0
; #define LAS __attribute__((address_space(3)))
; __device__ __forceinline__ unsigned cvt_pk_bf16(float lo, float hi) { const f32x2 v = {lo, hi}; const bf16x2_t r = __builtin_convertvector(v, bf16x2_t); return __builtin_bit_cast(unsigned, r); }
; __device__ __forceinline__ void gla_c_tile(LAS unsigned char* lds, const GlaArgs& A, int tile, int tid) {
;     ...
;       if (cc < 128) { const int d = cc & 63; const bool isq = cc < 64; LAS bf16_t* T1 = isq ? QG : KR; LAS bf16_t* T2 = isq ? QR : KG; const float sc = isq ? 0.125f : 1.0f;
; #pragma unroll
;           for (int e = 0; e < 8; ++e) { const int i = i0 + 8 * e; f32x4 x1, x2;
; #pragma unroll
;               for (int q = 0; q < 4; ++q) { const float eg = __expf(GC[i * 65 + d + q]); const float x = o[e][q] * sc; x1[q] = x * eg; x2[q] = x / eg; }
;               u32x2 w1, w2; w1.x = cvt_pk_bf16(x1[0], x1[1]); w1.y = cvt_pk_bf16(x1[2], x1[3]); w2.x = cvt_pk_bf16(x2[0], x2[1]); w2.y = cvt_pk_bf16(x2[2], x2[3]);
;               *(LAS u32x2*)(T1 + i * 72 + d) = w1; *(LAS u32x2*)(T2 + i * 72 + d) = w2; } }
	v_fmac_f32_e32 v15, v16, v15
	v_div_scale_f32 v16, vcc, v14, v12, v14
	v_mul_f32_e32 v17, v16, v15
	v_fma_f32 v33, -v13, v17, v16
	v_fmac_f32_e32 v17, v33, v15
	v_fma_f32 v13, -v13, v17, v16
	v_div_fmas_f32 v13, v13, v15, v17
	v_div_fixup_f32 v33, v13, v12, v14
	v_add_u32_e32 v12, 0x828, v147
	v_pk_mul_f32 v[14:15], v[98:99], v[30:31]
	v_mul_f32_e32 v13, 0x3fb8aa3b, v183
	v_exp_f32_e32 v13, v13
	v_mul_f32_e32 v12, 0x3fb8aa3b, v182
	v_exp_f32_e32 v12, v12
	v_div_scale_f32 v30, s[72:73], v13, v13, v15
	v_rcp_f32_e32 v31, v30
	v_pk_mul_f32 v[16:17], v[14:15], v[12:13]
	v_fma_f32 v34, -v30, v31, 1.0
	v_fmac_f32_e32 v31, v34, v31
	v_div_scale_f32 v34, vcc, v15, v13, v15
	v_mul_f32_e32 v35, v34, v31
	v_fma_f32 v36, -v30, v35, v34
	v_fmac_f32_e32 v35, v36, v31
	v_fma_f32 v30, -v30, v35, v34
	v_div_fmas_f32 v30, v30, v31, v35
	v_div_fixup_f32 v13, v30, v13, v15
	v_div_scale_f32 v15, s[72:73], v12, v12, v14
	v_rcp_f32_e32 v30, v15
	v_cvt_pk_bf16_f32 v11, v16, v17
	v_fma_f32 v31, -v15, v30, 1.0
	v_fmac_f32_e32 v30, v31, v30
	v_div_scale_f32 v31, vcc, v14, v12, v14
	v_mul_f32_e32 v34, v31, v30
	v_fma_f32 v35, -v15, v34, v31
	v_fmac_f32_e32 v34, v35, v30
	v_fma_f32 v15, -v15, v34, v31
	v_div_fmas_f32 v15, v15, v30, v34
	v_div_fixup_f32 v14, v15, v12, v14
	v_cvt_pk_bf16_f32 v12, v33, v32
	v_cvt_pk_bf16_f32 v13, v14, v13
	ds_write_b64 v140, v[10:11] offset:2304
	ds_write_b64 v141, v[12:13] offset:2304
	v_add_u32_e32 v10, 0x1040, v147
	v_pk_mul_f32 v[14:15], v[98:99], v[28:29]
	v_mul_f32_e32 v10, 0x3fb8aa3b, v184
	v_exp_f32_e32 v12, v10
	v_mul_f32_e32 v10, 0x3fb8aa3b, v185
	v_exp_f32_e32 v13, v10
	s_nop 0
	v_div_scale_f32 v16, s[72:73], v13, v13, v15
	v_rcp_f32_e32 v17, v16
	v_pk_mul_f32 v[10:11], v[14:15], v[12:13]
	v_fma_f32 v28, -v16, v17, 1.0
	v_fmac_f32_e32 v17, v28, v17
	v_div_scale_f32 v28, vcc, v15, v13, v15
	v_mul_f32_e32 v29, v28, v17
	v_fma_f32 v30, -v16, v29, v28
	v_fmac_f32_e32 v29, v30, v17
	v_fma_f32 v16, -v16, v29, v28
	v_div_fmas_f32 v16, v16, v17, v29
	v_div_fixup_f32 v28, v16, v13, v15
	v_div_scale_f32 v13, s[72:73], v12, v12, v14
	v_rcp_f32_e32 v15, v13
	v_cvt_pk_bf16_f32 v10, v10, v11
	v_fma_f32 v16, -v13, v15, 1.0
	v_fmac_f32_e32 v15, v16, v15
	v_div_scale_f32 v16, vcc, v14, v12, v14
	v_mul_f32_e32 v17, v16, v15
	v_fma_f32 v29, -v13, v17, v16
	v_fmac_f32_e32 v17, v29, v15
	v_fma_f32 v13, -v13, v17, v16
	v_div_fmas_f32 v13, v13, v15, v17
	v_div_fixup_f32 v29, v13, v12, v14
	v_add_u32_e32 v12, 0x1048, v147
	v_pk_mul_f32 v[14:15], v[98:99], v[24:25]
	v_mul_f32_e32 v13, 0x3fb8aa3b, v189
	v_exp_f32_e32 v13, v13
	v_mul_f32_e32 v12, 0x3fb8aa3b, v188
	v_exp_f32_e32 v12, v12
	v_div_scale_f32 v24, s[72:73], v13, v13, v15
	v_rcp_f32_e32 v25, v24
	v_pk_mul_f32 v[16:17], v[14:15], v[12:13]
	v_fma_f32 v30, -v24, v25, 1.0
	v_fmac_f32_e32 v25, v30, v25
	v_div_scale_f32 v30, vcc, v15, v13, v15
	v_mul_f32_e32 v31, v30, v25
	v_fma_f32 v32, -v24, v31, v30
	v_fmac_f32_e32 v31, v32, v25
	v_fma_f32 v24, -v24, v31, v30
	v_div_fmas_f32 v24, v24, v25, v31
	v_div_fixup_f32 v13, v24, v13, v15
	v_div_scale_f32 v15, s[72:73], v12, v12, v14
	v_rcp_f32_e32 v24, v15
	v_cvt_pk_bf16_f32 v11, v16, v17
	v_fma_f32 v25, -v15, v24, 1.0
	v_fmac_f32_e32 v24, v25, v24
	v_div_scale_f32 v25, vcc, v14, v12, v14
	v_mul_f32_e32 v30, v25, v24
	v_fma_f32 v31, -v15, v30, v25
	v_fmac_f32_e32 v30, v31, v24
	v_fma_f32 v15, -v15, v30, v25
	v_div_fmas_f32 v15, v15, v24, v30
	v_div_fixup_f32 v14, v15, v12, v14
	v_cvt_pk_bf16_f32 v12, v29, v28
	v_cvt_pk_bf16_f32 v13, v14, v13
	ds_write_b64 v140, v[10:11] offset:3456
	ds_write_b64 v141, v[12:13] offset:3456
	v_add_u32_e32 v10, 0x1860, v147
	v_add_u32_e32 v126, 0x1860, v147
	ds_read2_b32 v[128:129], v126 offset1:1
	v_add_u32_e32 v127, 0x1868, v147
	ds_read2_b32 v[130:131], v127 offset1:1
	v_add_u32_e32 v174, 0x2080, v147
	ds_read2_b32 v[176:177], v174 offset1:1
	v_add_u32_e32 v175, 0x2088, v147
	ds_read2_b32 v[178:179], v175 offset1:1
	v_add_u32_e32 v180, 0x28a0, v147
	ds_read2_b32 v[182:183], v180 offset1:1
	v_add_u32_e32 v181, 0x28a8, v147
	ds_read2_b32 v[184:185], v181 offset1:1
	v_add_u32_e32 v186, 0x30c0, v147
	ds_read2_b32 v[188:189], v186 offset1:1
	v_add_u32_e32 v187, 0x30c8, v147
	ds_read2_b32 v[190:191], v187 offset1:1
	s_waitcnt lgkmcnt(0)
	v_pk_mul_f32 v[14:15], v[98:99], v[26:27]
	v_mul_f32_e32 v10, 0x3fb8aa3b, v128
	v_exp_f32_e32 v12, v10
	v_mul_f32_e32 v10, 0x3fb8aa3b, v129
	v_exp_f32_e32 v13, v10
	s_nop 0
	v_div_scale_f32 v16, s[72:73], v13, v13, v15
	v_rcp_f32_e32 v17, v16
	v_pk_mul_f32 v[10:11], v[14:15], v[12:13]
	v_fma_f32 v24, -v16, v17, 1.0
	v_fmac_f32_e32 v17, v24, v17
	v_div_scale_f32 v24, vcc, v15, v13, v15
	v_mul_f32_e32 v25, v24, v17
	v_fma_f32 v26, -v16, v25, v24
	v_fmac_f32_e32 v25, v26, v17
	v_fma_f32 v16, -v16, v25, v24
	v_div_fmas_f32 v16, v16, v17, v25
	v_div_fixup_f32 v24, v16, v13, v15
	v_div_scale_f32 v13, s[72:73], v12, v12, v14
	v_rcp_f32_e32 v15, v13
	v_cvt_pk_bf16_f32 v10, v10, v11
	v_fma_f32 v16, -v13, v15, 1.0
	v_fmac_f32_e32 v15, v16, v15
	v_div_scale_f32 v16, vcc, v14, v12, v14
	v_mul_f32_e32 v17, v16, v15
	v_fma_f32 v25, -v13, v17, v16
	v_fmac_f32_e32 v17, v25, v15
	v_fma_f32 v13, -v13, v17, v16
	v_div_fmas_f32 v13, v13, v15, v17
	v_div_fixup_f32 v25, v13, v12, v14
	v_add_u32_e32 v12, 0x1868, v147
	v_pk_mul_f32 v[14:15], v[98:99], v[22:23]
	v_mul_f32_e32 v13, 0x3fb8aa3b, v131
	v_exp_f32_e32 v13, v13
	v_mul_f32_e32 v12, 0x3fb8aa3b, v130
	v_exp_f32_e32 v12, v12
	v_div_scale_f32 v22, s[72:73], v13, v13, v15
	v_rcp_f32_e32 v23, v22
	v_pk_mul_f32 v[16:17], v[14:15], v[12:13]
	v_fma_f32 v26, -v22, v23, 1.0
	v_fmac_f32_e32 v23, v26, v23
	v_div_scale_f32 v26, vcc, v15, v13, v15
	v_mul_f32_e32 v27, v26, v23
; #define LAS __attribute__((address_space(3)))
; __device__ __forceinline__ unsigned cvt_pk_bf16(float lo, float hi) { const f32x2 v = {lo, hi}; const bf16x2_t r = __builtin_convertvector(v, bf16x2_t); return __builtin_bit_cast(unsigned, r); }
; __device__ __forceinline__ void gla_c_tile(LAS unsigned char* lds, const GlaArgs& A, int tile, int tid) {
;     ...
;       if (cc < 128) { const int d = cc & 63; const bool isq = cc < 64; LAS bf16_t* T1 = isq ? QG : KR; LAS bf16_t* T2 = isq ? QR : KG; const float sc = isq ? 0.125f : 1.0f;
; #pragma unroll
;           for (int e = 0; e < 8; ++e) { const int i = i0 + 8 * e; f32x4 x1, x2;
; #pragma unroll
;               for (int q = 0; q < 4; ++q) { const float eg = __expf(GC[i * 65 + d + q]); const float x = o[e][q] * sc; x1[q] = x * eg; x2[q] = x / eg; }
;               u32x2 w1, w2; w1.x = cvt_pk_bf16(x1[0], x1[1]); w1.y = cvt_pk_bf16(x1[2], x1[3]); w2.x = cvt_pk_bf16(x2[0], x2[1]); w2.y = cvt_pk_bf16(x2[2], x2[3]);
;               *(LAS u32x2*)(T1 + i * 72 + d) = w1; *(LAS u32x2*)(T2 + i * 72 + d) = w2; } }
	v_fma_f32 v28, -v22, v27, v26
	v_fmac_f32_e32 v27, v28, v23
	v_fma_f32 v22, -v22, v27, v26
	v_div_fmas_f32 v22, v22, v23, v27
	v_div_fixup_f32 v13, v22, v13, v15
	v_div_scale_f32 v15, s[72:73], v12, v12, v14
	v_rcp_f32_e32 v22, v15
	v_cvt_pk_bf16_f32 v11, v16, v17
	v_fma_f32 v23, -v15, v22, 1.0
	v_fmac_f32_e32 v22, v23, v22
	v_div_scale_f32 v23, vcc, v14, v12, v14
	v_mul_f32_e32 v26, v23, v22
	v_fma_f32 v27, -v15, v26, v23
	v_fmac_f32_e32 v26, v27, v22
	v_fma_f32 v15, -v15, v26, v23
	v_div_fmas_f32 v15, v15, v22, v26
	v_div_fixup_f32 v14, v15, v12, v14
	v_cvt_pk_bf16_f32 v12, v25, v24
	v_cvt_pk_bf16_f32 v13, v14, v13
	ds_write_b64 v140, v[10:11] offset:4608
	ds_write_b64 v141, v[12:13] offset:4608
	v_add_u32_e32 v10, 0x2080, v147
	v_pk_mul_f32 v[14:15], v[98:99], v[20:21]
	v_mul_f32_e32 v10, 0x3fb8aa3b, v176
	v_exp_f32_e32 v12, v10
	v_mul_f32_e32 v10, 0x3fb8aa3b, v177
	v_exp_f32_e32 v13, v10
	s_nop 0
	v_div_scale_f32 v16, s[72:73], v13, v13, v15
	v_rcp_f32_e32 v17, v16
	v_pk_mul_f32 v[10:11], v[14:15], v[12:13]
	v_fma_f32 v20, -v16, v17, 1.0
	v_fmac_f32_e32 v17, v20, v17
	v_div_scale_f32 v20, vcc, v15, v13, v15
	v_mul_f32_e32 v21, v20, v17
	v_fma_f32 v22, -v16, v21, v20
	v_fmac_f32_e32 v21, v22, v17
	v_fma_f32 v16, -v16, v21, v20
	v_div_fmas_f32 v16, v16, v17, v21
	v_div_fixup_f32 v20, v16, v13, v15
	v_div_scale_f32 v13, s[72:73], v12, v12, v14
	v_rcp_f32_e32 v15, v13
	v_cvt_pk_bf16_f32 v10, v10, v11
	v_fma_f32 v16, -v13, v15, 1.0
	v_fmac_f32_e32 v15, v16, v15
	v_div_scale_f32 v16, vcc, v14, v12, v14
	v_mul_f32_e32 v17, v16, v15
	v_fma_f32 v21, -v13, v17, v16
	v_fmac_f32_e32 v17, v21, v15
	v_fma_f32 v13, -v13, v17, v16
	v_div_fmas_f32 v13, v13, v15, v17
	v_div_fixup_f32 v21, v13, v12, v14
	v_add_u32_e32 v12, 0x2088, v147
	v_pk_mul_f32 v[14:15], v[98:99], v[18:19]
	v_mul_f32_e32 v13, 0x3fb8aa3b, v179
	v_exp_f32_e32 v13, v13
	v_mul_f32_e32 v12, 0x3fb8aa3b, v178
	v_exp_f32_e32 v12, v12
	v_div_scale_f32 v18, s[72:73], v13, v13, v15
	v_rcp_f32_e32 v19, v18
	v_pk_mul_f32 v[16:17], v[14:15], v[12:13]
	v_fma_f32 v22, -v18, v19, 1.0
	v_fmac_f32_e32 v19, v22, v19
	v_div_scale_f32 v22, vcc, v15, v13, v15
	v_mul_f32_e32 v23, v22, v19
	v_fma_f32 v24, -v18, v23, v22
	v_fmac_f32_e32 v23, v24, v19
	v_fma_f32 v18, -v18, v23, v22
	v_div_fmas_f32 v18, v18, v19, v23
	v_div_fixup_f32 v13, v18, v13, v15
	v_div_scale_f32 v15, s[72:73], v12, v12, v14
	v_rcp_f32_e32 v18, v15
	v_cvt_pk_bf16_f32 v11, v16, v17
	v_fma_f32 v19, -v15, v18, 1.0
	v_fmac_f32_e32 v18, v19, v18
	v_div_scale_f32 v19, vcc, v14, v12, v14
	v_mul_f32_e32 v22, v19, v18
	v_fma_f32 v23, -v15, v22, v19
	v_fmac_f32_e32 v22, v23, v18
	v_fma_f32 v15, -v15, v22, v19
	v_div_fmas_f32 v15, v15, v18, v22
	v_div_fixup_f32 v14, v15, v12, v14
	v_cvt_pk_bf16_f32 v12, v21, v20
	v_cvt_pk_bf16_f32 v13, v14, v13
	ds_write_b64 v140, v[10:11] offset:5760
	ds_write_b64 v141, v[12:13] offset:5760
	v_add_u32_e32 v10, 0x28a0, v147
	v_pk_mul_f32 v[12:13], v[98:99], v[8:9]
	v_mul_f32_e32 v8, 0x3fb8aa3b, v183
	v_exp_f32_e32 v11, v8
	v_mul_f32_e32 v10, 0x3fb8aa3b, v182
	v_exp_f32_e32 v10, v10
	v_div_scale_f32 v14, s[72:73], v11, v11, v13
	v_rcp_f32_e32 v15, v14
	v_pk_mul_f32 v[8:9], v[12:13], v[10:11]
	v_fma_f32 v16, -v14, v15, 1.0
	v_fmac_f32_e32 v15, v16, v15
	v_div_scale_f32 v16, vcc, v13, v11, v13
	v_mul_f32_e32 v17, v16, v15
	v_fma_f32 v18, -v14, v17, v16
	v_fmac_f32_e32 v17, v18, v15
	v_fma_f32 v14, -v14, v17, v16
	v_div_fmas_f32 v14, v14, v15, v17
	v_div_fixup_f32 v14, v14, v11, v13
	v_div_scale_f32 v11, s[72:73], v10, v10, v12
	v_rcp_f32_e32 v13, v11
	s_nop 0
	v_fma_f32 v15, -v11, v13, 1.0
	v_fmac_f32_e32 v13, v15, v13
	v_div_scale_f32 v15, vcc, v12, v10, v12
	v_mul_f32_e32 v16, v15, v13
	v_fma_f32 v17, -v11, v16, v15
	v_fmac_f32_e32 v16, v17, v13
	v_fma_f32 v11, -v11, v16, v15
	v_div_fmas_f32 v11, v11, v13, v16
	v_div_fixup_f32 v15, v11, v10, v12
	v_add_u32_e32 v10, 0x28a8, v147
	v_mul_f32_e32 v11, 0x3fb8aa3b, v185
	v_exp_f32_e32 v11, v11
	v_mul_f32_e32 v10, 0x3fb8aa3b, v184
	v_exp_f32_e32 v10, v10
	v_div_scale_f32 v16, s[72:73], v11, v11, v7
	v_rcp_f32_e32 v17, v16
	v_pk_mul_f32 v[12:13], v[6:7], v[10:11]
	v_fma_f32 v18, -v16, v17, 1.0
	v_fmac_f32_e32 v17, v18, v17
	v_div_scale_f32 v18, vcc, v7, v11, v7
	v_mul_f32_e32 v19, v18, v17
	v_fma_f32 v20, -v16, v19, v18
	v_fmac_f32_e32 v19, v20, v17
	v_fma_f32 v16, -v16, v19, v18
	v_div_fmas_f32 v16, v16, v17, v19
	v_div_fixup_f32 v11, v16, v11, v7
	v_div_scale_f32 v7, s[72:73], v10, v10, v6
	v_rcp_f32_e32 v16, v7
	s_nop 0
	v_fma_f32 v17, -v7, v16, 1.0
	v_fmac_f32_e32 v16, v17, v16
	v_div_scale_f32 v17, vcc, v6, v10, v6
	v_mul_f32_e32 v18, v17, v16
	v_fma_f32 v19, -v7, v18, v17
	v_fmac_f32_e32 v18, v19, v16
	v_fma_f32 v7, -v7, v18, v17
	v_div_fmas_f32 v7, v7, v16, v18
	v_div_fixup_f32 v10, v7, v10, v6
	v_cvt_pk_bf16_f32 v6, v8, v9
	v_cvt_pk_bf16_f32 v7, v12, v13
	v_cvt_pk_bf16_f32 v8, v15, v14
	v_cvt_pk_bf16_f32 v9, v10, v11
	ds_write_b64 v140, v[6:7] offset:6912
	ds_write_b64 v141, v[8:9] offset:6912
	v_add_u32_e32 v6, 0x30c0, v147
	v_pk_mul_f32 v[8:9], v[98:99], v[4:5]
	v_mul_f32_e32 v4, 0x3fb8aa3b, v189
	v_exp_f32_e32 v7, v4
	v_mul_f32_e32 v6, 0x3fb8aa3b, v188
	v_exp_f32_e32 v6, v6
	v_div_scale_f32 v10, s[72:73], v7, v7, v9
	v_rcp_f32_e32 v11, v10
	v_pk_mul_f32 v[4:5], v[8:9], v[6:7]
	v_fma_f32 v12, -v10, v11, 1.0
	v_fmac_f32_e32 v11, v12, v11
	v_div_scale_f32 v12, vcc, v9, v7, v9
	v_mul_f32_e32 v13, v12, v11
	v_fma_f32 v14, -v10, v13, v12
	v_fmac_f32_e32 v13, v14, v11
	v_fma_f32 v10, -v10, v13, v12
	v_div_fmas_f32 v10, v10, v11, v13
	v_div_fixup_f32 v10, v10, v7, v9
	v_div_scale_f32 v7, s[72:73], v6, v6, v8
	v_rcp_f32_e32 v9, v7
	s_nop 0
	v_fma_f32 v11, -v7, v9, 1.0
	v_fmac_f32_e32 v9, v11, v9
	v_div_scale_f32 v11, vcc, v8, v6, v8
	v_mul_f32_e32 v12, v11, v9
	v_fma_f32 v13, -v7, v12, v11
	v_fmac_f32_e32 v12, v13, v9
	v_fma_f32 v7, -v7, v12, v11
	v_div_fmas_f32 v7, v7, v9, v12
	v_div_fixup_f32 v11, v7, v6, v8
	v_add_u32_e32 v6, 0x30c8, v147
	v_mul_f32_e32 v7, 0x3fb8aa3b, v191
	v_exp_f32_e32 v7, v7
	v_mul_f32_e32 v6, 0x3fb8aa3b, v190
	v_exp_f32_e32 v6, v6
	v_div_scale_f32 v12, s[72:73], v7, v7, v3
	v_rcp_f32_e32 v13, v12
	v_pk_mul_f32 v[8:9], v[2:3], v[6:7]
	v_fma_f32 v14, -v12, v13, 1.0
	v_fmac_f32_e32 v13, v14, v13
	v_div_scale_f32 v14, vcc, v3, v7, v3
	v_mul_f32_e32 v15, v14, v13
	v_fma_f32 v16, -v12, v15, v14
	v_fmac_f32_e32 v15, v16, v13
	v_fma_f32 v12, -v12, v15, v14
	v_div_fmas_f32 v12, v12, v13, v15
	v_div_fixup_f32 v7, v12, v7, v3
	v_div_scale_f32 v3, s[72:73], v6, v6, v2
	v_rcp_f32_e32 v12, v3
	s_nop 0
	v_fma_f32 v13, -v3, v12, 1.0
	v_fmac_f32_e32 v12, v13, v12
	v_div_scale_f32 v13, vcc, v2, v6, v2
	v_mul_f32_e32 v14, v13, v12
	v_fma_f32 v15, -v3, v14, v13
	v_fmac_f32_e32 v14, v15, v12
	v_fma_f32 v3, -v3, v14, v13
	v_div_fmas_f32 v3, v3, v12, v14
	v_div_fixup_f32 v6, v3, v6, v2
	v_cvt_pk_bf16_f32 v2, v4, v5
	v_cvt_pk_bf16_f32 v3, v8, v9
	v_cvt_pk_bf16_f32 v4, v11, v10
	v_cvt_pk_bf16_f32 v5, v6, v7
	ds_write_b64 v140, v[2:3] offset:8064
	ds_write_b64 v141, v[4:5] offset:8064
